# k30: k29 + grid barriers 2-5 use a shorter protocol (returning arrive on XCD counter, XCD-last writes back L2 and bumps one global word that every block polls)
# speedup vs baseline: 1.0110x; 1.0110x over previous
; __device__ __forceinline__ unsigned xb_ld(unsigned* p)              { return __hip_atomic_load(p, __ATOMIC_RELAXED, __HIP_MEMORY_SCOPE_AGENT); }
; __device__ __forceinline__ unsigned xb_add(unsigned* p, unsigned v) { return __hip_atomic_fetch_add(p, v, __ATOMIC_RELAXED, __HIP_MEMORY_SCOPE_AGENT); }
; #define XB_SPIN(cond, bar) do { unsigned _sp = 0; while (cond) { __builtin_amdgcn_s_sleep(1); \
;     if ((++_sp & 255u) == 0u) { if (xb_ld(&(bar)[XB_TMO])) break; if (_sp > XB_SPIN_CAP) { atomicAdd(&(bar)[XB_TMO], 1u); break; } } } } while (0)
; __device__ __forceinline__ void xcd_barrier(const XcdBarrier& b) {
;     asm volatile("s_waitcnt vmcnt(0)" ::: "memory");
;     __syncthreads();
;     if (threadIdx.x == 0) {
;         unsigned* bar = b.bar;
;         __builtin_amdgcn_s_waitcnt(0);
;         unsigned nloc = b.st[0], nx = b.st[1];
;         if (nloc == 0u) { xcd_barrier_complete(bar, b.x, nloc, nx); b.st[0] = nloc; b.st[1] = nx; }
;         const unsigned old = xb_add(&bar[XB_XSUB(b.x)], 1u);
;         const unsigned gen = old / nloc;
;         if (old + 1u == (gen + 1u) * nloc) {
;             __builtin_amdgcn_fence(__ATOMIC_RELEASE, "agent");
;             asm volatile("s_waitcnt vmcnt(0)" ::: "memory");
;             const unsigned og = xb_add(&bar[XB_TOP], 1u);
;             const unsigned tg = og / nx;
;             if (og + 1u == (tg + 1u) * nx) xb_add(&bar[XB_TOPGEN], 1u);
;             else XB_SPIN(xb_ld(&bar[XB_TOPGEN]) == tg, bar);
;             __builtin_amdgcn_fence(__ATOMIC_ACQUIRE, "agent");
;             xb_add(&bar[XB_XGEN(b.x)], 1u);
;             asm volatile("s_waitcnt vmcnt(0)" ::: "memory");
;         } else {
;             XB_SPIN(xb_ld(&bar[XB_XGEN(b.x)]) == gen, bar);
;             __builtin_amdgcn_fence(__ATOMIC_ACQUIRE, "agent");
;             asm volatile("s_waitcnt vmcnt(0)" ::: "memory");
;         }
;     }
;     __syncthreads();
; }
.LBB0_150:
	s_waitcnt vmcnt(0)
	s_barrier
	s_mov_b64 s[0:1], exec
	v_readlane_b32 s4, v255, 4
	v_readlane_b32 s5, v255, 5
	s_and_b64 s[4:5], s[0:1], s[4:5]
	s_xor_b64 s[0:1], s[4:5], s[0:1]
	s_mov_b64 exec, s[4:5]
	s_cbranch_execz .LBB0_203
	s_add_i32 s8, 0, 0x20160
	v_mov_b32_e32 v0, s8
	ds_read_b32 v2, v0
	ds_read_b32 v3, v0 offset:4
	v_readlane_b32 s9, v255, 3
	v_mov_b32_e32 v1, 1
	s_lshl_b32 s9, s9, 8
	s_add_i32 s9, s9, 0x8000
	v_mov_b32_e32 v0, s9
	s_waitcnt vmcnt(0) lgkmcnt(0)
	global_atomic_add v4, v0, v1, s[92:93] sc0
	v_readfirstlane_b32 s10, v2
	v_readfirstlane_b32 s11, v3
	s_nop 3
	s_mul_i32 s10, s10, 1
	s_mul_i32 s11, s11, 1
	s_waitcnt vmcnt(0)
	v_readfirstlane_b32 s12, v4
	s_nop 3
	s_add_i32 s12, s12, 1
	s_cmp_lg_u32 s12, s10
	s_cbranch_scc1 .Lmy_gb1_wait
	buffer_wbl2 sc1
	s_waitcnt vmcnt(0) lgkmcnt(0)
	v_mov_b32_e32 v0, 0x9000
	global_atomic_add v0, v1, s[92:93]
.Lmy_gb1_wait:
	v_mov_b32_e32 v0, 0x9000
	s_mov_b32 s13, 0
.Lmy_gb1_spin:
	global_load_dword v5, v0, s[92:93] sc1
	s_add_u32 s13, s13, 1
	s_waitcnt vmcnt(0)
	v_readfirstlane_b32 s12, v5
	s_nop 3
	s_cmp_ge_u32 s12, s11
	s_cbranch_scc1 .Lmy_gb1_done
	s_cmp_gt_u32 s13, 0x2000
	s_cbranch_scc1 .Lmy_gb1_done
	s_sleep 1
	s_branch .Lmy_gb1_spin
.Lmy_gb1_done:
	buffer_inv sc1
	s_waitcnt vmcnt(0)

; __device__ __forceinline__ unsigned xb_ld(unsigned* p)              { return __hip_atomic_load(p, __ATOMIC_RELAXED, __HIP_MEMORY_SCOPE_AGENT); }
; __device__ __forceinline__ unsigned xb_add(unsigned* p, unsigned v) { return __hip_atomic_fetch_add(p, v, __ATOMIC_RELAXED, __HIP_MEMORY_SCOPE_AGENT); }
; #define XB_SPIN(cond, bar) do { unsigned _sp = 0; while (cond) { __builtin_amdgcn_s_sleep(1); \
;     if ((++_sp & 255u) == 0u) { if (xb_ld(&(bar)[XB_TMO])) break; if (_sp > XB_SPIN_CAP) { atomicAdd(&(bar)[XB_TMO], 1u); break; } } } } while (0)
; __device__ __forceinline__ void xcd_barrier(const XcdBarrier& b) {
;     asm volatile("s_waitcnt vmcnt(0)" ::: "memory");
;     __syncthreads();
;     if (threadIdx.x == 0) {
;         unsigned* bar = b.bar;
;         __builtin_amdgcn_s_waitcnt(0);
;         unsigned nloc = b.st[0], nx = b.st[1];
;         if (nloc == 0u) { xcd_barrier_complete(bar, b.x, nloc, nx); b.st[0] = nloc; b.st[1] = nx; }
;         const unsigned old = xb_add(&bar[XB_XSUB(b.x)], 1u);
;         const unsigned gen = old / nloc;
;         if (old + 1u == (gen + 1u) * nloc) {
;             __builtin_amdgcn_fence(__ATOMIC_RELEASE, "agent");
;             asm volatile("s_waitcnt vmcnt(0)" ::: "memory");
;             const unsigned og = xb_add(&bar[XB_TOP], 1u);
;             const unsigned tg = og / nx;
;             if (og + 1u == (tg + 1u) * nx) xb_add(&bar[XB_TOPGEN], 1u);
;             else XB_SPIN(xb_ld(&bar[XB_TOPGEN]) == tg, bar);
;             __builtin_amdgcn_fence(__ATOMIC_ACQUIRE, "agent");
;             xb_add(&bar[XB_XGEN(b.x)], 1u);
;             asm volatile("s_waitcnt vmcnt(0)" ::: "memory");
;         } else {
;             XB_SPIN(xb_ld(&bar[XB_XGEN(b.x)]) == gen, bar);
;             __builtin_amdgcn_fence(__ATOMIC_ACQUIRE, "agent");
;             asm volatile("s_waitcnt vmcnt(0)" ::: "memory");
;         }
;     }
;     __syncthreads();
; }
.LBB0_549:
	s_waitcnt vmcnt(0)
	s_waitcnt vmcnt(0)
	s_barrier
	s_mov_b64 s[0:1], exec
	v_readlane_b32 s4, v255, 4
	v_readlane_b32 s5, v255, 5
	s_and_b64 s[4:5], s[0:1], s[4:5]
	s_xor_b64 s[0:1], s[4:5], s[0:1]
	s_mov_b64 exec, s[4:5]
	s_cbranch_execz .LBB0_602
	s_add_i32 s8, 0, 0x20160
	v_mov_b32_e32 v0, s8
	ds_read_b32 v2, v0
	ds_read_b32 v3, v0 offset:4
	v_readlane_b32 s9, v255, 3
	v_mov_b32_e32 v1, 1
	s_lshl_b32 s9, s9, 8
	s_add_i32 s9, s9, 0x8000
	v_mov_b32_e32 v0, s9
	s_waitcnt vmcnt(0) lgkmcnt(0)
	global_atomic_add v4, v0, v1, s[92:93] sc0
	v_readfirstlane_b32 s10, v2
	v_readfirstlane_b32 s11, v3
	s_nop 3
	s_mul_i32 s10, s10, 2
	s_mul_i32 s11, s11, 2
	s_waitcnt vmcnt(0)
	v_readfirstlane_b32 s12, v4
	s_nop 3
	s_add_i32 s12, s12, 1
	s_cmp_lg_u32 s12, s10
	s_cbranch_scc1 .Lmy_gb2_wait
	buffer_wbl2 sc1
	s_waitcnt vmcnt(0) lgkmcnt(0)
	v_mov_b32_e32 v0, 0x9000
	global_atomic_add v0, v1, s[92:93]

; __device__ __forceinline__ unsigned xb_ld(unsigned* p)              { return __hip_atomic_load(p, __ATOMIC_RELAXED, __HIP_MEMORY_SCOPE_AGENT); }
; __device__ __forceinline__ unsigned xb_add(unsigned* p, unsigned v) { return __hip_atomic_fetch_add(p, v, __ATOMIC_RELAXED, __HIP_MEMORY_SCOPE_AGENT); }
; #define XB_SPIN(cond, bar) do { unsigned _sp = 0; while (cond) { __builtin_amdgcn_s_sleep(1); \
;     if ((++_sp & 255u) == 0u) { if (xb_ld(&(bar)[XB_TMO])) break; if (_sp > XB_SPIN_CAP) { atomicAdd(&(bar)[XB_TMO], 1u); break; } } } } while (0)
; __device__ __forceinline__ void xcd_barrier(const XcdBarrier& b) {
;     asm volatile("s_waitcnt vmcnt(0)" ::: "memory");
;     __syncthreads();
;     if (threadIdx.x == 0) {
;         unsigned* bar = b.bar;
;         __builtin_amdgcn_s_waitcnt(0);
;         unsigned nloc = b.st[0], nx = b.st[1];
;         if (nloc == 0u) { xcd_barrier_complete(bar, b.x, nloc, nx); b.st[0] = nloc; b.st[1] = nx; }
;         const unsigned old = xb_add(&bar[XB_XSUB(b.x)], 1u);
;         const unsigned gen = old / nloc;
;         if (old + 1u == (gen + 1u) * nloc) {
;             __builtin_amdgcn_fence(__ATOMIC_RELEASE, "agent");
;             asm volatile("s_waitcnt vmcnt(0)" ::: "memory");
;             const unsigned og = xb_add(&bar[XB_TOP], 1u);
;             const unsigned tg = og / nx;
;             if (og + 1u == (tg + 1u) * nx) xb_add(&bar[XB_TOPGEN], 1u);
;             else XB_SPIN(xb_ld(&bar[XB_TOPGEN]) == tg, bar);
;             __builtin_amdgcn_fence(__ATOMIC_ACQUIRE, "agent");
;             xb_add(&bar[XB_XGEN(b.x)], 1u);
;             asm volatile("s_waitcnt vmcnt(0)" ::: "memory");
;         } else {
;             XB_SPIN(xb_ld(&bar[XB_XGEN(b.x)]) == gen, bar);
;             __builtin_amdgcn_fence(__ATOMIC_ACQUIRE, "agent");
;             asm volatile("s_waitcnt vmcnt(0)" ::: "memory");
;         }
;     }
;     __syncthreads();
; }
.LBB0_908:
	s_waitcnt vmcnt(0)
	s_waitcnt vmcnt(0)
	s_barrier
	s_mov_b64 s[0:1], exec
	v_readlane_b32 s6, v255, 4
	v_readlane_b32 s7, v255, 5
	s_and_b64 s[6:7], s[0:1], s[6:7]
	s_xor_b64 s[0:1], s[6:7], s[0:1]
	s_mov_b64 exec, s[6:7]
	s_cbranch_execz .LBB0_961
	s_add_i32 s8, 0, 0x20160
	v_mov_b32_e32 v0, s8
	ds_read_b32 v2, v0
	ds_read_b32 v3, v0 offset:4
	v_readlane_b32 s9, v255, 3
	v_mov_b32_e32 v1, 1
	s_lshl_b32 s9, s9, 8
	s_add_i32 s9, s9, 0x8000
	v_mov_b32_e32 v0, s9
	s_waitcnt vmcnt(0) lgkmcnt(0)
	global_atomic_add v4, v0, v1, s[92:93] sc0
	v_readfirstlane_b32 s10, v2
	v_readfirstlane_b32 s11, v3
	s_nop 3
	s_mul_i32 s10, s10, 3
	s_mul_i32 s11, s11, 3
	s_waitcnt vmcnt(0)
	v_readfirstlane_b32 s12, v4
	s_nop 3
	s_add_i32 s12, s12, 1
	s_cmp_lg_u32 s12, s10
	s_cbranch_scc1 .Lmy_gb3_wait
	buffer_wbl2 sc1
	s_waitcnt vmcnt(0) lgkmcnt(0)
	v_mov_b32_e32 v0, 0x9000
	global_atomic_add v0, v1, s[92:93]

; __device__ __forceinline__ unsigned xb_ld(unsigned* p)              { return __hip_atomic_load(p, __ATOMIC_RELAXED, __HIP_MEMORY_SCOPE_AGENT); }
; __device__ __forceinline__ unsigned xb_add(unsigned* p, unsigned v) { return __hip_atomic_fetch_add(p, v, __ATOMIC_RELAXED, __HIP_MEMORY_SCOPE_AGENT); }
; #define XB_SPIN(cond, bar) do { unsigned _sp = 0; while (cond) { __builtin_amdgcn_s_sleep(1); \
;     if ((++_sp & 255u) == 0u) { if (xb_ld(&(bar)[XB_TMO])) break; if (_sp > XB_SPIN_CAP) { atomicAdd(&(bar)[XB_TMO], 1u); break; } } } } while (0)
; __device__ __forceinline__ void xcd_barrier(const XcdBarrier& b) {
;     asm volatile("s_waitcnt vmcnt(0)" ::: "memory");
;     __syncthreads();
;     if (threadIdx.x == 0) {
;         unsigned* bar = b.bar;
;         __builtin_amdgcn_s_waitcnt(0);
;         unsigned nloc = b.st[0], nx = b.st[1];
;         if (nloc == 0u) { xcd_barrier_complete(bar, b.x, nloc, nx); b.st[0] = nloc; b.st[1] = nx; }
;         const unsigned old = xb_add(&bar[XB_XSUB(b.x)], 1u);
;         const unsigned gen = old / nloc;
;         if (old + 1u == (gen + 1u) * nloc) {
;             __builtin_amdgcn_fence(__ATOMIC_RELEASE, "agent");
;             asm volatile("s_waitcnt vmcnt(0)" ::: "memory");
;             const unsigned og = xb_add(&bar[XB_TOP], 1u);
;             const unsigned tg = og / nx;
;             if (og + 1u == (tg + 1u) * nx) xb_add(&bar[XB_TOPGEN], 1u);
;             else XB_SPIN(xb_ld(&bar[XB_TOPGEN]) == tg, bar);
;             __builtin_amdgcn_fence(__ATOMIC_ACQUIRE, "agent");
;             xb_add(&bar[XB_XGEN(b.x)], 1u);
;             asm volatile("s_waitcnt vmcnt(0)" ::: "memory");
;         } else {
;             XB_SPIN(xb_ld(&bar[XB_XGEN(b.x)]) == gen, bar);
;             __builtin_amdgcn_fence(__ATOMIC_ACQUIRE, "agent");
;             asm volatile("s_waitcnt vmcnt(0)" ::: "memory");
;         }
;     }
;     __syncthreads();
; }
.LBB0_981:
	s_waitcnt vmcnt(0)
	s_barrier
	s_mov_b64 s[0:1], exec
	v_readlane_b32 s4, v255, 4
	v_readlane_b32 s5, v255, 5
	s_and_b64 s[4:5], s[0:1], s[4:5]
	s_xor_b64 s[0:1], s[4:5], s[0:1]
	s_mov_b64 exec, s[4:5]
	s_cbranch_execz .LBB0_1034
	s_add_i32 s8, 0, 0x20160
	v_mov_b32_e32 v0, s8
	ds_read_b32 v2, v0
	ds_read_b32 v3, v0 offset:4
	v_readlane_b32 s9, v255, 3
	v_mov_b32_e32 v1, 1
	s_lshl_b32 s9, s9, 8
	s_add_i32 s9, s9, 0x8000
	v_mov_b32_e32 v0, s9
	s_waitcnt vmcnt(0) lgkmcnt(0)
	global_atomic_add v4, v0, v1, s[92:93] sc0
	v_readfirstlane_b32 s10, v2
	v_readfirstlane_b32 s11, v3
	s_nop 3
	s_mul_i32 s10, s10, 4
	s_mul_i32 s11, s11, 4
	s_waitcnt vmcnt(0)
	v_readfirstlane_b32 s12, v4
	s_nop 3
	s_add_i32 s12, s12, 1
	s_cmp_lg_u32 s12, s10
	s_cbranch_scc1 .Lmy_gb4_wait
	buffer_wbl2 sc1
	s_waitcnt vmcnt(0) lgkmcnt(0)
	v_mov_b32_e32 v0, 0x9000
	global_atomic_add v0, v1, s[92:93]
